# grid barrier: the three-quarter-th arriver of each XCD issues an extra unwaited L2 write-back
# speedup vs baseline: 1.0048x; 1.0048x over previous
.LBB0_691:
	v_readlane_b32 s8, v239, 18
	v_readlane_b32 s9, v239, 19
	s_add_u32 s8, s6, s8
	s_addc_u32 s9, s7, s9
	v_mov_b64_e32 v[4:5], s[8:9]
	flat_atomic_add v3, v[4:5], v185 sc0
	v_cvt_f32_u32_e32 v1, v2
	v_sub_u32_e32 v4, 0, v2
	v_rcp_iflag_f32_e32 v1, v1
	s_nop 0
	v_mul_f32_e32 v1, 0x4f7ffffe, v1
	v_cvt_u32_f32_e32 v1, v1
	v_mul_lo_u32 v4, v4, v1
	v_mul_hi_u32 v4, v1, v4
	v_add_u32_e32 v1, v1, v4
	s_waitcnt vmcnt(0) lgkmcnt(0)
	v_mul_hi_u32 v1, v3, v1
	v_mul_lo_u32 v4, v1, v2
	v_sub_u32_e32 v4, v3, v4
	v_cmp_ge_u32_e32 vcc, v4, v2
	v_add_u32_e32 v5, 1, v1
	s_nop 0
	v_cndmask_b32_e32 v1, v1, v5, vcc
	v_sub_u32_e32 v5, v4, v2
	v_cndmask_b32_e32 v4, v4, v5, vcc
	v_cmp_ge_u32_e32 vcc, v4, v2
	v_add_u32_e32 v4, 1, v1
	s_nop 0
	v_cndmask_b32_e32 v1, v1, v4, vcc
	v_mul_lo_u32 v5, v1, v2
	v_lshrrev_b32_e32 v4, 2, v2
	v_sub_u32_e32 v5, v3, v5
	v_sub_u32_e32 v4, v2, v4
	v_cmp_eq_u32_e32 vcc, v5, v4
	s_cbranch_vccz .Lxb_nomid
	buffer_wbl2 sc1
.Lxb_nomid:
	v_add_u32_e32 v4, 1, v3
	v_mad_u64_u32 v[2:3], s[8:9], v2, v1, v[2:3]
	v_cmp_ne_u32_e32 vcc, v4, v2
	s_and_saveexec_b64 s[8:9], vcc
	s_xor_b64 s[8:9], exec, s[8:9]
	s_cbranch_execz .LBB0_704
	s_add_u32 s12, s6, 0x3500
	s_addc_u32 s13, s7, 0
	v_mov_b64_e32 v[2:3], s[12:13]
	flat_load_dword v0, v[2:3] sc1
	s_waitcnt vmcnt(0) lgkmcnt(0)
	v_cmp_eq_u32_e32 vcc, v0, v1
	s_and_saveexec_b64 s[10:11], vcc
	s_cbranch_execz .LBB0_703
	s_mov_b32 s28, 1
	s_mov_b64 s[14:15], 0
	s_branch .LBB0_695
